# P0 gamma-folded weight transposes: 32 serialized load round trips per item batched (all W loads in flight), plus attention micro-edits
# speedup vs baseline: 1.0256x; 1.0083x over previous
; #define ALDS __attribute__((address_space(3)))
; template <bool F16> __device__ __forceinline__ void transpose_item(const float* W, int K, int N, int type, const float* gk, bf16* WT, ALDS float* scr, int item, int lane) {
;     const int nblk = N / 32, kb = item / nblk, nb = item % nblk, k0 = 64 * kb, n0 = 32 * nb;
;     const int sc = src_col(type, n0 + (lane & 31));
; #pragma unroll
;     for (int i = 0; i < 32; ++i) { const int kk = 2 * i + (lane >> 5); scr[kk * 33 + (lane & 31)] = W[(size_t)(k0 + kk) * N + sc] * (gk ? gk[k0 + kk] : 1.0f); }
; __global__ void __launch_bounds__(NWAVES * 64, 2) fwd_megakernel(Args args) {
;     ...
;             if (r < I1) { transpose_item<true>(args.in[9] + (size_t)l * D * 2 * FF, D, 2 * FF, 1, args.in[11] + (size_t)(l * 3 + 1) * D, (bf16*)(wl + W3_OFF), scr, r, lane); continue; } r -= I1;
.LBB0_16:
	s_andn2_b64 vcc, exec, s[4:5]
	s_cbranch_vccnz .LBB0_82
	s_mul_i32 s4, s38, 0x1600000
	s_mul_hi_i32 s5, s38, 0x1600000
	s_add_u32 s4, s12, s4
	s_mul_i32 s40, s38, 3
	s_addc_u32 s5, s13, s5
	s_ashr_i32 s41, s40, 31
	s_lshl_b64 s[40:41], s[40:41], 12
	s_add_u32 s28, s6, s40
	s_addc_u32 s41, s7, s41
	s_add_u32 s40, s28, 0x1000
	s_addc_u32 s41, s41, 0
	s_add_i32 s28, s42, 0xe900
	s_and_b32 s43, s28, 0xffff
	s_mul_i32 s43, s43, 0xba2f
	s_lshr_b32 s43, s43, 23
	s_mul_i32 s58, s43, 0xb0
	s_sub_i32 s28, s28, s58
	s_and_b32 s58, s28, 0xffff
	s_lshl_b32 s28, s58, 5
	s_lshl_b32 s43, s43, 6
	s_and_b32 s59, s28, 0xe0
	s_cmpk_lt_u32 s59, 0x80
	s_cselect_b64 vcc, -1, 0
	s_lshl_b32 s58, s58, 4
	v_or_b32_e32 v6, s59, v74
	s_and_b32 s58, s58, 0xf80
	v_or_b32_e32 v8, s58, v6
	s_addk_i32 s58, 0xa80
	v_add_u32_e32 v6, s58, v6
	v_cndmask_b32_e32 v6, v6, v8, vcc
	v_lshlrev_b32_e32 v6, 2, v6
	v_lshl_add_u64 v[8:9], s[4:5], 0, v[6:7]
	v_or_b32_e32 v162, s43, v2
	v_mad_u64_u32 v[164:165], s[58:59], v162, s53, v[8:9]
	global_load_dword v114, v[164:165], off
	v_or_b32_e32 v163, s43, v13
	v_mad_u64_u32 v[166:167], s[58:59], v163, s53, v[8:9]
	global_load_dword v115, v[166:167], off
	v_or_b32_e32 v162, s43, v15
	v_mad_u64_u32 v[164:165], s[58:59], v162, s53, v[8:9]
	global_load_dword v116, v[164:165], off
	v_or_b32_e32 v163, s43, v17
	v_mad_u64_u32 v[166:167], s[58:59], v163, s53, v[8:9]
	global_load_dword v117, v[166:167], off
	v_or_b32_e32 v162, s43, v19
	v_mad_u64_u32 v[164:165], s[58:59], v162, s53, v[8:9]
	global_load_dword v118, v[164:165], off
	v_or_b32_e32 v163, s43, v21
	v_mad_u64_u32 v[166:167], s[58:59], v163, s53, v[8:9]
	global_load_dword v119, v[166:167], off
	v_or_b32_e32 v162, s43, v23
	v_mad_u64_u32 v[164:165], s[58:59], v162, s53, v[8:9]
	global_load_dword v120, v[164:165], off
	v_or_b32_e32 v163, s43, v25
	v_mad_u64_u32 v[166:167], s[58:59], v163, s53, v[8:9]
	global_load_dword v121, v[166:167], off
	v_or_b32_e32 v162, s43, v27
	v_mad_u64_u32 v[164:165], s[58:59], v162, s53, v[8:9]
	global_load_dword v122, v[164:165], off
	v_or_b32_e32 v163, s43, v29
	v_mad_u64_u32 v[166:167], s[58:59], v163, s53, v[8:9]
	global_load_dword v123, v[166:167], off
	v_or_b32_e32 v162, s43, v31
	v_mad_u64_u32 v[164:165], s[58:59], v162, s53, v[8:9]
	global_load_dword v124, v[164:165], off
	v_or_b32_e32 v163, s43, v33
	v_mad_u64_u32 v[166:167], s[58:59], v163, s53, v[8:9]
	global_load_dword v125, v[166:167], off
	v_or_b32_e32 v162, s43, v36
	v_mad_u64_u32 v[164:165], s[58:59], v162, s53, v[8:9]
	global_load_dword v126, v[164:165], off
	v_or_b32_e32 v163, s43, v38
	v_mad_u64_u32 v[166:167], s[58:59], v163, s53, v[8:9]
	global_load_dword v127, v[166:167], off
	v_or_b32_e32 v162, s43, v40
	v_mad_u64_u32 v[164:165], s[58:59], v162, s53, v[8:9]
	global_load_dword v128, v[164:165], off
	v_or_b32_e32 v163, s43, v42
	v_mad_u64_u32 v[166:167], s[58:59], v163, s53, v[8:9]
	global_load_dword v129, v[166:167], off
	v_or_b32_e32 v162, s43, v44
	v_mad_u64_u32 v[164:165], s[58:59], v162, s53, v[8:9]
	global_load_dword v130, v[164:165], off
	v_or_b32_e32 v163, s43, v46
	v_mad_u64_u32 v[166:167], s[58:59], v163, s53, v[8:9]
	global_load_dword v131, v[166:167], off
	v_or_b32_e32 v162, s43, v48
	v_mad_u64_u32 v[164:165], s[58:59], v162, s53, v[8:9]
	global_load_dword v132, v[164:165], off
	v_or_b32_e32 v163, s43, v50
	v_mad_u64_u32 v[166:167], s[58:59], v163, s53, v[8:9]
	global_load_dword v133, v[166:167], off
	v_or_b32_e32 v162, s43, v52
	v_mad_u64_u32 v[164:165], s[58:59], v162, s53, v[8:9]
	global_load_dword v134, v[164:165], off
	v_or_b32_e32 v163, s43, v54
	v_mad_u64_u32 v[166:167], s[58:59], v163, s53, v[8:9]
	global_load_dword v135, v[166:167], off
	v_or_b32_e32 v162, s43, v62
	v_mad_u64_u32 v[164:165], s[58:59], v162, s53, v[8:9]
	global_load_dword v136, v[164:165], off
	v_or_b32_e32 v163, s43, v63
	v_mad_u64_u32 v[166:167], s[58:59], v163, s53, v[8:9]
	global_load_dword v137, v[166:167], off
	v_or_b32_e32 v162, s43, v64
	v_mad_u64_u32 v[164:165], s[58:59], v162, s53, v[8:9]
	global_load_dword v138, v[164:165], off
	v_or_b32_e32 v163, s43, v65
	v_mad_u64_u32 v[166:167], s[58:59], v163, s53, v[8:9]
	global_load_dword v139, v[166:167], off
	v_or_b32_e32 v162, s43, v66
	v_mad_u64_u32 v[164:165], s[58:59], v162, s53, v[8:9]
	global_load_dword v140, v[164:165], off
	v_or_b32_e32 v163, s43, v67
	v_mad_u64_u32 v[166:167], s[58:59], v163, s53, v[8:9]
	global_load_dword v141, v[166:167], off
	v_or_b32_e32 v162, s43, v68
	v_mad_u64_u32 v[164:165], s[58:59], v162, s53, v[8:9]
	global_load_dword v142, v[164:165], off
	v_or_b32_e32 v163, s43, v69
	v_mad_u64_u32 v[166:167], s[58:59], v163, s53, v[8:9]
	global_load_dword v143, v[166:167], off
	v_or_b32_e32 v162, s43, v70
	v_mad_u64_u32 v[164:165], s[58:59], v162, s53, v[8:9]
	global_load_dword v144, v[164:165], off
	v_or_b32_e32 v163, s43, v71
	v_mad_u64_u32 v[166:167], s[58:59], v163, s53, v[8:9]
	global_load_dword v145, v[166:167], off
	v_add_lshl_u32 v6, v2, s43, 2
	v_mov_b32_e32 v146, 1.0
	v_mov_b32_e32 v147, 1.0
	v_mov_b32_e32 v148, 1.0
	v_mov_b32_e32 v149, 1.0
	v_mov_b32_e32 v150, 1.0
	v_mov_b32_e32 v151, 1.0
	v_mov_b32_e32 v152, 1.0
	v_mov_b32_e32 v153, 1.0
	v_mov_b32_e32 v154, 1.0
	v_mov_b32_e32 v155, 1.0
	v_mov_b32_e32 v156, 1.0
	v_mov_b32_e32 v157, 1.0
	v_mov_b32_e32 v158, 1.0
	v_mov_b32_e32 v159, 1.0
	v_mov_b32_e32 v160, 1.0
	v_mov_b32_e32 v161, 1.0
	s_andn2_b64 vcc, exec, s[20:21]
	s_cbranch_vccnz .LtrA_nogk1
	global_load_dword v146, v6, s[40:41]
	global_load_dword v147, v6, s[40:41] offset:8
	global_load_dword v148, v6, s[40:41] offset:16
	global_load_dword v149, v6, s[40:41] offset:24
	global_load_dword v150, v6, s[40:41] offset:32
	global_load_dword v151, v6, s[40:41] offset:40
	global_load_dword v152, v6, s[40:41] offset:48
	global_load_dword v153, v6, s[40:41] offset:56
	global_load_dword v154, v6, s[40:41] offset:64
	global_load_dword v155, v6, s[40:41] offset:72
	global_load_dword v156, v6, s[40:41] offset:80
	global_load_dword v157, v6, s[40:41] offset:88
	global_load_dword v158, v6, s[40:41] offset:96
	global_load_dword v159, v6, s[40:41] offset:104
	global_load_dword v160, v6, s[40:41] offset:112
	global_load_dword v161, v6, s[40:41] offset:120
; __device__ __forceinline__ unsigned cvtpk(float lo, float hi) { f32x2_t v = {lo, hi}; bf16x2_t b = __builtin_convertvector(v, bf16x2_t); return __builtin_bit_cast(unsigned, b); }
; #define ALDS __attribute__((address_space(3)))
; template <bool F16> __device__ __forceinline__ void transpose_item(const float* W, int K, int N, int type, const float* gk, bf16* WT, ALDS float* scr, int item, int lane) {
;     ...
;     for (int i = 0; i < 32; ++i) { const int kk = 2 * i + (lane >> 5); scr[kk * 33 + (lane & 31)] = W[(size_t)(k0 + kk) * N + sc] * (gk ? gk[k0 + kk] : 1.0f); }
;     asm volatile("s_waitcnt lgkmcnt(0)" ::: "memory");
;     const int c = lane & 7;
; #pragma unroll
;     for (int j = 0; j < 4; ++j) { const int n = (lane >> 3) + 8 * j; const ALDS float* s = scr + (8 * c) * 33 + n;
;         v4u o; if (F16) { o.x = pg8::cvtpk_h(s[0 * 33], s[1 * 33]); o.y = pg8::cvtpk_h(s[2 * 33], s[3 * 33]); o.z = pg8::cvtpk_h(s[4 * 33], s[5 * 33]); o.w = pg8::cvtpk_h(s[6 * 33], s[7 * 33]); }
;         else { o.x = cvtpk(s[0 * 33], s[1 * 33]); o.y = cvtpk(s[2 * 33], s[3 * 33]); o.z = cvtpk(s[4 * 33], s[5 * 33]); o.w = cvtpk(s[6 * 33], s[7 * 33]); }
;         *(v4u*)(WT + (size_t)(n0 + n) * K + k0 + 8 * c) = o; }
;     asm volatile("s_waitcnt lgkmcnt(0)" ::: "memory");
.LtrA_nogk1:
	s_waitcnt vmcnt(0)
	v_add_u32_e32 v168, v5, v58
	v_mul_f32_e32 v114, v114, v146
	v_add_u32_e32 v162, v5, v12
	ds_write_b32 v162, v114
	v_mul_f32_e32 v115, v115, v147
	v_add_u32_e32 v163, v5, v14
	ds_write_b32 v163, v115
	v_mul_f32_e32 v116, v116, v148
	v_add_u32_e32 v169, v5, v16
	ds_write_b32 v169, v116
	v_mul_f32_e32 v117, v117, v149
	v_add_u32_e32 v170, v5, v18
	ds_write_b32 v170, v117
	v_mul_f32_e32 v118, v118, v150
	v_add_u32_e32 v162, v5, v20
	ds_write_b32 v162, v118
	v_mul_f32_e32 v119, v119, v151
	v_add_u32_e32 v163, v5, v22
	ds_write_b32 v163, v119
	v_mul_f32_e32 v120, v120, v152
	v_add_u32_e32 v169, v5, v24
	ds_write_b32 v169, v120
	v_mul_f32_e32 v121, v121, v153
	v_add_u32_e32 v170, v5, v26
	ds_write_b32 v170, v121
	v_mul_f32_e32 v122, v122, v154
	v_add_u32_e32 v162, v5, v28
	ds_write_b32 v162, v122
	v_mul_f32_e32 v123, v123, v155
	v_add_u32_e32 v163, v5, v30
	ds_write_b32 v163, v123
	v_mul_f32_e32 v124, v124, v156
	v_add_u32_e32 v169, v5, v32
	ds_write_b32 v169, v124
	v_mul_f32_e32 v125, v125, v157
	v_add_u32_e32 v170, v5, v35
	ds_write_b32 v170, v125
	v_mul_f32_e32 v126, v126, v158
	v_add_u32_e32 v162, v5, v37
	ds_write_b32 v162, v126
	v_mul_f32_e32 v127, v127, v159
	v_add_u32_e32 v163, v5, v39
	ds_write_b32 v163, v127
	v_mul_f32_e32 v128, v128, v160
	v_add_u32_e32 v169, v5, v41
	ds_write_b32 v169, v128
	v_mul_f32_e32 v129, v129, v161
	v_add_u32_e32 v170, v5, v43
	ds_write_b32 v170, v129
	s_andn2_b64 vcc, exec, s[20:21]
	s_cbranch_vccnz .LtrA_nogk2
	global_load_dword v146, v6, s[40:41] offset:128
	global_load_dword v147, v6, s[40:41] offset:136
	global_load_dword v148, v6, s[40:41] offset:144
	global_load_dword v149, v6, s[40:41] offset:152
	global_load_dword v150, v6, s[40:41] offset:160
	global_load_dword v151, v6, s[40:41] offset:168
	global_load_dword v152, v6, s[40:41] offset:176
	global_load_dword v153, v6, s[40:41] offset:184
	global_load_dword v154, v6, s[40:41] offset:192
	global_load_dword v155, v6, s[40:41] offset:200
	global_load_dword v156, v6, s[40:41] offset:208
	global_load_dword v157, v6, s[40:41] offset:216
	global_load_dword v158, v6, s[40:41] offset:224
	global_load_dword v159, v6, s[40:41] offset:232
	global_load_dword v160, v6, s[40:41] offset:240
	global_load_dword v161, v6, s[40:41] offset:248
	s_waitcnt vmcnt(0)
.LtrA_nogk2:
	v_mul_f32_e32 v130, v130, v146
	v_add_u32_e32 v162, v5, v45
	ds_write_b32 v162, v130
	v_mul_f32_e32 v131, v131, v147
	v_add_u32_e32 v163, v5, v47
	ds_write_b32 v163, v131
	v_mul_f32_e32 v132, v132, v148
	v_add_u32_e32 v169, v5, v49
	ds_write_b32 v169, v132
	v_mul_f32_e32 v133, v133, v149
	v_add_u32_e32 v170, v5, v51
	ds_write_b32 v170, v133
	v_mul_f32_e32 v134, v134, v150
	v_add_u32_e32 v162, v5, v53
	ds_write_b32 v162, v134
	v_mul_f32_e32 v135, v135, v151
	v_add_u32_e32 v163, v5, v55
	ds_write_b32 v163, v135
	v_mul_f32_e32 v136, v136, v152
	v_add_u32_e32 v169, v5, v56
	ds_write_b32 v169, v136
	v_mul_f32_e32 v137, v137, v153
	v_add_u32_e32 v170, v5, v57
	ds_write_b32 v170, v137
	v_mul_f32_e32 v138, v138, v154
	v_add_u32_e32 v162, v5, v58
	ds_write_b32 v162, v138
	v_mul_f32_e32 v139, v139, v155
	ds_write_b32 v168, v139 offset:264
	v_mul_f32_e32 v140, v140, v156
	ds_write_b32 v168, v140 offset:528
	v_mul_f32_e32 v141, v141, v157
	ds_write_b32 v168, v141 offset:792
	v_mul_f32_e32 v142, v142, v158
	ds_write_b32 v168, v142 offset:1056
	v_mul_f32_e32 v143, v143, v159
	ds_write_b32 v168, v143 offset:1320
	v_mul_f32_e32 v144, v144, v160
	ds_write_b32 v168, v144 offset:1584
	v_mul_f32_e32 v145, v145, v161
	ds_write_b32 v168, v145 offset:1848
	s_waitcnt lgkmcnt(0)
	s_lshl_b32 s4, s43, 1
	ds_read2_b32 v[78:79], v60 offset0:33 offset1:41
	ds_read2_b32 v[80:81], v60 offset1:8
	ds_read2_b32 v[82:83], v60 offset0:66 offset1:74
	ds_read2_b32 v[84:85], v60 offset0:99 offset1:107
	ds_read2_b32 v[86:87], v60 offset0:132 offset1:140
	ds_read2_b32 v[88:89], v60 offset0:165 offset1:173
	ds_read2_b32 v[90:91], v60 offset0:198 offset1:206
	ds_read2_b32 v[92:93], v60 offset0:231 offset1:239
	s_add_u32 s4, s56, s4
	s_addc_u32 s5, s57, 0
	v_lshlrev_b32_e32 v6, 1, v4
	v_lshl_add_u64 v[8:9], s[4:5], 0, v[6:7]
	v_or_b32_e32 v6, s28, v59
	v_lshl_add_u64 v[94:95], v[8:9], 0, s[24:25]
	v_lshlrev_b32_e32 v6, 11, v6
	s_waitcnt lgkmcnt(6)
	v_cvt_pk_f16_f32 v8, v80, v78
	s_waitcnt lgkmcnt(4)
	v_cvt_pk_f16_f32 v9, v82, v84
	s_waitcnt lgkmcnt(2)
	v_cvt_pk_f16_f32 v10, v86, v88
	s_waitcnt lgkmcnt(0)
	v_cvt_pk_f16_f32 v11, v90, v92
	v_lshl_add_u64 v[96:97], v[94:95], 0, v[6:7]
	global_store_dwordx4 v[96:97], v[8:11], off
	v_or_b32_e32 v6, s28, v72
	v_lshlrev_b32_e32 v6, 11, v6
	v_cvt_pk_f16_f32 v8, v81, v79
	v_cvt_pk_f16_f32 v9, v83, v85
	v_cvt_pk_f16_f32 v10, v87, v89
	v_cvt_pk_f16_f32 v11, v91, v93
	ds_read2_b32 v[80:81], v60 offset0:49 offset1:57
	ds_read2_b32 v[82:83], v60 offset0:16 offset1:24
	ds_read2_b32 v[84:85], v60 offset0:82 offset1:90
	ds_read2_b32 v[86:87], v60 offset0:115 offset1:123
	ds_read2_b32 v[88:89], v60 offset0:148 offset1:156
	ds_read2_b32 v[90:91], v60 offset0:181 offset1:189
	ds_read2_b32 v[92:93], v60 offset0:214 offset1:222
	ds_read2_b32 v[96:97], v60 offset0:247 offset1:255
	v_lshl_add_u64 v[78:79], v[94:95], 0, v[6:7]
	v_or_b32_e32 v6, s28, v73
	v_lshlrev_b32_e32 v6, 11, v6
	global_store_dwordx4 v[78:79], v[8:11], off
	v_lshl_add_u64 v[78:79], v[94:95], 0, v[6:7]
	v_or_b32_e32 v6, s28, v75
	s_waitcnt lgkmcnt(6)
	v_cvt_pk_f16_f32 v8, v82, v80
	s_waitcnt lgkmcnt(4)
	v_cvt_pk_f16_f32 v9, v84, v86
	s_waitcnt lgkmcnt(2)
	v_cvt_pk_f16_f32 v10, v88, v90
	s_waitcnt lgkmcnt(0)
	v_cvt_pk_f16_f32 v11, v92, v96
	v_lshlrev_b32_e32 v6, 11, v6
	global_store_dwordx4 v[78:79], v[8:11], off
	v_lshl_add_u64 v[78:79], v[94:95], 0, v[6:7]
	s_nop 0
	v_cvt_pk_f16_f32 v8, v83, v81
	v_cvt_pk_f16_f32 v9, v85, v87
	v_cvt_pk_f16_f32 v10, v89, v91
	v_cvt_pk_f16_f32 v11, v93, v97
	global_store_dwordx4 v[78:79], v[8:11], off
	s_waitcnt lgkmcnt(0)

; #define ALDS __attribute__((address_space(3)))
; template <bool F16> __device__ __forceinline__ void transpose_item(const float* W, int K, int N, int type, const float* gk, bf16* WT, ALDS float* scr, int item, int lane) {
;     const int nblk = N / 32, kb = item / nblk, nb = item % nblk, k0 = 64 * kb, n0 = 32 * nb;
;     const int sc = src_col(type, n0 + (lane & 31));
; #pragma unroll
;     for (int i = 0; i < 32; ++i) { const int kk = 2 * i + (lane >> 5); scr[kk * 33 + (lane & 31)] = W[(size_t)(k0 + kk) * N + sc] * (gk ? gk[k0 + kk] : 1.0f); }
; __global__ void __launch_bounds__(NWAVES * 64, 2) fwd_megakernel(Args args) {
;     ...
;             if (r < I3) { transpose_item<true>(args.in[2] + (size_t)l * D * NIN, D, NIN, 2, args.in[11] + (size_t)(l * 3) * D, (bf16*)(wl + WIN_OFF), scr, r, lane); continue; } r -= I3;
.LBB0_86:
	s_andn2_b64 vcc, exec, s[4:5]
	s_cbranch_vccnz .LBB0_152
	s_mul_i32 s4, s38, 0x900000
	s_mul_hi_i32 s5, s38, 0x900000
	s_add_u32 s4, s16, s4
	s_mul_i32 s40, s38, 3
	s_addc_u32 s5, s17, s5
	s_ashr_i32 s41, s40, 31
	s_lshl_b64 s[40:41], s[40:41], 12
	s_add_u32 s40, s6, s40
	s_addc_u32 s41, s7, s41
	s_add_i32 s28, s42, 0xef80
	s_and_b32 s39, s28, 0xffff
	s_mul_i32 s39, s39, 0xe38f
	s_lshr_b32 s43, s39, 16
	s_lshr_b32 s39, s39, 22
	s_mulk_i32 s39, 0x48
	s_sub_i32 s58, s28, s39
	s_and_b32 s39, s43, 0xffc0
	s_lshl_b32 s43, s58, 5
	s_and_b32 s28, s43, 0xffe0
	s_and_b32 s58, s58, 0xffff
	s_cmp_lt_u32 s58, 32
	s_cselect_b64 s[58:59], -1, 0
	s_add_i32 s60, s43, 0xfa00
	s_and_b32 s60, s60, 0xffe0
	v_or_b32_e32 v6, s28, v74
	s_cmpk_lt_u32 s60, 0x280
	s_cselect_b64 s[60:61], -1, 0
	s_and_b32 s43, s43, 0xfc0
	v_bfe_u32 v8, v6, 1, 5
	v_or3_b32 v8, s43, v61, v8
	s_or_b64 vcc, s[58:59], s[60:61]
	v_cndmask_b32_e32 v6, v6, v8, vcc
	v_lshlrev_b32_e32 v6, 2, v6
	v_lshl_add_u64 v[8:9], s[4:5], 0, v[6:7]
	v_or_b32_e32 v162, s39, v2
	v_mad_u64_u32 v[164:165], s[58:59], v162, s54, v[8:9]
	global_load_dword v114, v[164:165], off
	v_or_b32_e32 v163, s39, v13
	v_mad_u64_u32 v[166:167], s[58:59], v163, s54, v[8:9]
	global_load_dword v115, v[166:167], off
	v_or_b32_e32 v162, s39, v15
	v_mad_u64_u32 v[164:165], s[58:59], v162, s54, v[8:9]
	global_load_dword v116, v[164:165], off
	v_or_b32_e32 v163, s39, v17
	v_mad_u64_u32 v[166:167], s[58:59], v163, s54, v[8:9]
	global_load_dword v117, v[166:167], off
	v_or_b32_e32 v162, s39, v19
	v_mad_u64_u32 v[164:165], s[58:59], v162, s54, v[8:9]
	global_load_dword v118, v[164:165], off
	v_or_b32_e32 v163, s39, v21
	v_mad_u64_u32 v[166:167], s[58:59], v163, s54, v[8:9]
	global_load_dword v119, v[166:167], off
	v_or_b32_e32 v162, s39, v23
	v_mad_u64_u32 v[164:165], s[58:59], v162, s54, v[8:9]
	global_load_dword v120, v[164:165], off
	v_or_b32_e32 v163, s39, v25
	v_mad_u64_u32 v[166:167], s[58:59], v163, s54, v[8:9]
	global_load_dword v121, v[166:167], off
	v_or_b32_e32 v162, s39, v27
	v_mad_u64_u32 v[164:165], s[58:59], v162, s54, v[8:9]
	global_load_dword v122, v[164:165], off
	v_or_b32_e32 v163, s39, v29
	v_mad_u64_u32 v[166:167], s[58:59], v163, s54, v[8:9]
	global_load_dword v123, v[166:167], off
	v_or_b32_e32 v162, s39, v31
	v_mad_u64_u32 v[164:165], s[58:59], v162, s54, v[8:9]
	global_load_dword v124, v[164:165], off
	v_or_b32_e32 v163, s39, v33
	v_mad_u64_u32 v[166:167], s[58:59], v163, s54, v[8:9]
	global_load_dword v125, v[166:167], off
	v_or_b32_e32 v162, s39, v36
	v_mad_u64_u32 v[164:165], s[58:59], v162, s54, v[8:9]
	global_load_dword v126, v[164:165], off
	v_or_b32_e32 v163, s39, v38
	v_mad_u64_u32 v[166:167], s[58:59], v163, s54, v[8:9]
	global_load_dword v127, v[166:167], off
	v_or_b32_e32 v162, s39, v40
	v_mad_u64_u32 v[164:165], s[58:59], v162, s54, v[8:9]
	global_load_dword v128, v[164:165], off
	v_or_b32_e32 v163, s39, v42
	v_mad_u64_u32 v[166:167], s[58:59], v163, s54, v[8:9]
	global_load_dword v129, v[166:167], off
	v_or_b32_e32 v162, s39, v44
	v_mad_u64_u32 v[164:165], s[58:59], v162, s54, v[8:9]
	global_load_dword v130, v[164:165], off
	v_or_b32_e32 v163, s39, v46
	v_mad_u64_u32 v[166:167], s[58:59], v163, s54, v[8:9]
	global_load_dword v131, v[166:167], off
	v_or_b32_e32 v162, s39, v48
	v_mad_u64_u32 v[164:165], s[58:59], v162, s54, v[8:9]
	global_load_dword v132, v[164:165], off
	v_or_b32_e32 v163, s39, v50
	v_mad_u64_u32 v[166:167], s[58:59], v163, s54, v[8:9]
	global_load_dword v133, v[166:167], off
	v_or_b32_e32 v162, s39, v52
	v_mad_u64_u32 v[164:165], s[58:59], v162, s54, v[8:9]
	global_load_dword v134, v[164:165], off
	v_or_b32_e32 v163, s39, v54
	v_mad_u64_u32 v[166:167], s[58:59], v163, s54, v[8:9]
	global_load_dword v135, v[166:167], off
	v_or_b32_e32 v162, s39, v62
	v_mad_u64_u32 v[164:165], s[58:59], v162, s54, v[8:9]
	global_load_dword v136, v[164:165], off
	v_or_b32_e32 v163, s39, v63
	v_mad_u64_u32 v[166:167], s[58:59], v163, s54, v[8:9]
	global_load_dword v137, v[166:167], off
	v_or_b32_e32 v162, s39, v64
	v_mad_u64_u32 v[164:165], s[58:59], v162, s54, v[8:9]
	global_load_dword v138, v[164:165], off
	v_or_b32_e32 v163, s39, v65
	v_mad_u64_u32 v[166:167], s[58:59], v163, s54, v[8:9]
	global_load_dword v139, v[166:167], off
	v_or_b32_e32 v162, s39, v66
	v_mad_u64_u32 v[164:165], s[58:59], v162, s54, v[8:9]
	global_load_dword v140, v[164:165], off
	v_or_b32_e32 v163, s39, v67
	v_mad_u64_u32 v[166:167], s[58:59], v163, s54, v[8:9]
	global_load_dword v141, v[166:167], off
	v_or_b32_e32 v162, s39, v68
	v_mad_u64_u32 v[164:165], s[58:59], v162, s54, v[8:9]
	global_load_dword v142, v[164:165], off
	v_or_b32_e32 v163, s39, v69
	v_mad_u64_u32 v[166:167], s[58:59], v163, s54, v[8:9]
	global_load_dword v143, v[166:167], off
	v_or_b32_e32 v162, s39, v70
	v_mad_u64_u32 v[164:165], s[58:59], v162, s54, v[8:9]
	global_load_dword v144, v[164:165], off
	v_or_b32_e32 v163, s39, v71
	v_mad_u64_u32 v[166:167], s[58:59], v163, s54, v[8:9]
	global_load_dword v145, v[166:167], off
	v_add_lshl_u32 v6, v2, s39, 2
	v_mov_b32_e32 v146, 1.0
	v_mov_b32_e32 v147, 1.0
	v_mov_b32_e32 v148, 1.0
	v_mov_b32_e32 v149, 1.0
	v_mov_b32_e32 v150, 1.0
	v_mov_b32_e32 v151, 1.0
	v_mov_b32_e32 v152, 1.0
	v_mov_b32_e32 v153, 1.0
	v_mov_b32_e32 v154, 1.0
	v_mov_b32_e32 v155, 1.0
	v_mov_b32_e32 v156, 1.0
	v_mov_b32_e32 v157, 1.0
	v_mov_b32_e32 v158, 1.0
	v_mov_b32_e32 v159, 1.0
	v_mov_b32_e32 v160, 1.0
	v_mov_b32_e32 v161, 1.0
	s_andn2_b64 vcc, exec, s[20:21]
	s_cbranch_vccnz .LtrB_nogk1
	global_load_dword v146, v6, s[40:41]
	global_load_dword v147, v6, s[40:41] offset:8
	global_load_dword v148, v6, s[40:41] offset:16
	global_load_dword v149, v6, s[40:41] offset:24
	global_load_dword v150, v6, s[40:41] offset:32
	global_load_dword v151, v6, s[40:41] offset:40
	global_load_dword v152, v6, s[40:41] offset:48
	global_load_dword v153, v6, s[40:41] offset:56
	global_load_dword v154, v6, s[40:41] offset:64
	global_load_dword v155, v6, s[40:41] offset:72
	global_load_dword v156, v6, s[40:41] offset:80
	global_load_dword v157, v6, s[40:41] offset:88
	global_load_dword v158, v6, s[40:41] offset:96
	global_load_dword v159, v6, s[40:41] offset:104
	global_load_dword v160, v6, s[40:41] offset:112
	global_load_dword v161, v6, s[40:41] offset:120

; __device__ __forceinline__ unsigned cvtpk(float lo, float hi) { f32x2_t v = {lo, hi}; bf16x2_t b = __builtin_convertvector(v, bf16x2_t); return __builtin_bit_cast(unsigned, b); }
; #define ALDS __attribute__((address_space(3)))
; template <bool F16> __device__ __forceinline__ void transpose_item(const float* W, int K, int N, int type, const float* gk, bf16* WT, ALDS float* scr, int item, int lane) {
;     ...
;     for (int i = 0; i < 32; ++i) { const int kk = 2 * i + (lane >> 5); scr[kk * 33 + (lane & 31)] = W[(size_t)(k0 + kk) * N + sc] * (gk ? gk[k0 + kk] : 1.0f); }
;     asm volatile("s_waitcnt lgkmcnt(0)" ::: "memory");
;     const int c = lane & 7;
; #pragma unroll
;     for (int j = 0; j < 4; ++j) { const int n = (lane >> 3) + 8 * j; const ALDS float* s = scr + (8 * c) * 33 + n;
;         v4u o; if (F16) { o.x = pg8::cvtpk_h(s[0 * 33], s[1 * 33]); o.y = pg8::cvtpk_h(s[2 * 33], s[3 * 33]); o.z = pg8::cvtpk_h(s[4 * 33], s[5 * 33]); o.w = pg8::cvtpk_h(s[6 * 33], s[7 * 33]); }
;         else { o.x = cvtpk(s[0 * 33], s[1 * 33]); o.y = cvtpk(s[2 * 33], s[3 * 33]); o.z = cvtpk(s[4 * 33], s[5 * 33]); o.w = cvtpk(s[6 * 33], s[7 * 33]); }
;         *(v4u*)(WT + (size_t)(n0 + n) * K + k0 + 8 * c) = o; }
;     asm volatile("s_waitcnt lgkmcnt(0)" ::: "memory");
.LtrB_nogk2:
	v_mul_f32_e32 v130, v130, v146
	v_add_u32_e32 v162, v5, v45
	ds_write_b32 v162, v130
	v_mul_f32_e32 v131, v131, v147
	v_add_u32_e32 v163, v5, v47
	ds_write_b32 v163, v131
	v_mul_f32_e32 v132, v132, v148
	v_add_u32_e32 v169, v5, v49
	ds_write_b32 v169, v132
	v_mul_f32_e32 v133, v133, v149
	v_add_u32_e32 v170, v5, v51
	ds_write_b32 v170, v133
	v_mul_f32_e32 v134, v134, v150
	v_add_u32_e32 v162, v5, v53
	ds_write_b32 v162, v134
	v_mul_f32_e32 v135, v135, v151
	v_add_u32_e32 v163, v5, v55
	ds_write_b32 v163, v135
	v_mul_f32_e32 v136, v136, v152
	v_add_u32_e32 v169, v5, v56
	ds_write_b32 v169, v136
	v_mul_f32_e32 v137, v137, v153
	v_add_u32_e32 v170, v5, v57
	ds_write_b32 v170, v137
	v_mul_f32_e32 v138, v138, v154
	v_add_u32_e32 v162, v5, v58
	ds_write_b32 v162, v138
	v_mul_f32_e32 v139, v139, v155
	ds_write_b32 v168, v139 offset:264
	v_mul_f32_e32 v140, v140, v156
	ds_write_b32 v168, v140 offset:528
	v_mul_f32_e32 v141, v141, v157
	ds_write_b32 v168, v141 offset:792
	v_mul_f32_e32 v142, v142, v158
	ds_write_b32 v168, v142 offset:1056
	v_mul_f32_e32 v143, v143, v159
	ds_write_b32 v168, v143 offset:1320
	v_mul_f32_e32 v144, v144, v160
	ds_write_b32 v168, v144 offset:1584
	v_mul_f32_e32 v145, v145, v161
	ds_write_b32 v168, v145 offset:1848
	s_waitcnt lgkmcnt(0)
	s_lshl_b32 s4, s39, 1
	ds_read2_b32 v[78:79], v60 offset0:33 offset1:41
	ds_read2_b32 v[80:81], v60 offset1:8
	ds_read2_b32 v[82:83], v60 offset0:66 offset1:74
	ds_read2_b32 v[84:85], v60 offset0:99 offset1:107
	ds_read2_b32 v[86:87], v60 offset0:132 offset1:140
	ds_read2_b32 v[88:89], v60 offset0:165 offset1:173
	ds_read2_b32 v[90:91], v60 offset0:198 offset1:206
	ds_read2_b32 v[92:93], v60 offset0:231 offset1:239
	s_add_u32 s4, s56, s4
	s_addc_u32 s5, s57, 0
	v_lshlrev_b32_e32 v6, 1, v4
	v_lshl_add_u64 v[8:9], s[4:5], 0, v[6:7]
	v_or_b32_e32 v6, s28, v59
	v_lshl_add_u64 v[94:95], v[8:9], 0, s[34:35]
	v_lshlrev_b32_e32 v6, 11, v6
	s_waitcnt lgkmcnt(6)
	v_cvt_pk_f16_f32 v8, v80, v78
	s_waitcnt lgkmcnt(4)
	v_cvt_pk_f16_f32 v9, v82, v84
	s_waitcnt lgkmcnt(2)
	v_cvt_pk_f16_f32 v10, v86, v88
	s_waitcnt lgkmcnt(0)
	v_cvt_pk_f16_f32 v11, v90, v92
	v_lshl_add_u64 v[96:97], v[94:95], 0, v[6:7]
	global_store_dwordx4 v[96:97], v[8:11], off
	v_or_b32_e32 v6, s28, v72
	v_lshlrev_b32_e32 v6, 11, v6
	v_cvt_pk_f16_f32 v8, v81, v79
	v_cvt_pk_f16_f32 v9, v83, v85
	v_cvt_pk_f16_f32 v10, v87, v89
	v_cvt_pk_f16_f32 v11, v91, v93
	ds_read2_b32 v[80:81], v60 offset0:49 offset1:57
	ds_read2_b32 v[82:83], v60 offset0:16 offset1:24
	ds_read2_b32 v[84:85], v60 offset0:82 offset1:90
	ds_read2_b32 v[86:87], v60 offset0:115 offset1:123
	ds_read2_b32 v[88:89], v60 offset0:148 offset1:156
	ds_read2_b32 v[90:91], v60 offset0:181 offset1:189
	ds_read2_b32 v[92:93], v60 offset0:214 offset1:222
	ds_read2_b32 v[96:97], v60 offset0:247 offset1:255
	v_lshl_add_u64 v[78:79], v[94:95], 0, v[6:7]
	v_or_b32_e32 v6, s28, v73
	v_lshlrev_b32_e32 v6, 11, v6
	global_store_dwordx4 v[78:79], v[8:11], off
	v_lshl_add_u64 v[78:79], v[94:95], 0, v[6:7]
	v_or_b32_e32 v6, s28, v75
	s_waitcnt lgkmcnt(6)
	v_cvt_pk_f16_f32 v8, v82, v80
	s_waitcnt lgkmcnt(4)
	v_cvt_pk_f16_f32 v9, v84, v86
	s_waitcnt lgkmcnt(2)
	v_cvt_pk_f16_f32 v10, v88, v90
	s_waitcnt lgkmcnt(0)
	v_cvt_pk_f16_f32 v11, v92, v96
	v_lshlrev_b32_e32 v6, 11, v6
	global_store_dwordx4 v[78:79], v[8:11], off
	v_lshl_add_u64 v[78:79], v[94:95], 0, v[6:7]
	s_nop 0
	v_cvt_pk_f16_f32 v8, v83, v81
	v_cvt_pk_f16_f32 v9, v85, v87
	v_cvt_pk_f16_f32 v10, v89, v91
	v_cvt_pk_f16_f32 v11, v93, v97
	global_store_dwordx4 v[78:79], v[8:11], off
	s_waitcnt lgkmcnt(0)

; #define ALDS __attribute__((address_space(3)))
; template <bool F16> __device__ __forceinline__ void transpose_item(const float* W, int K, int N, int type, const float* gk, bf16* WT, ALDS float* scr, int item, int lane) {
;     const int nblk = N / 32, kb = item / nblk, nb = item % nblk, k0 = 64 * kb, n0 = 32 * nb;
;     const int sc = src_col(type, n0 + (lane & 31));
; #pragma unroll
;     for (int i = 0; i < 32; ++i) { const int kk = 2 * i + (lane >> 5); scr[kk * 33 + (lane & 31)] = W[(size_t)(k0 + kk) * N + sc] * (gk ? gk[k0 + kk] : 1.0f); }
; __global__ void __launch_bounds__(NWAVES * 64, 2) fwd_megakernel(Args args) {
;     ...
;             if (r < I1) { transpose_item<true>(args.in[7] + (size_t)l * D * 2 * FF, D, 2 * FF, 1, (l > 0) ? args.in[11] + (size_t)((l - 1) * 3 + 2) * D : nullptr, (bf16*)(wl + W1_OFF), scr, r, lane); continue; } r -= I1;
.LBB0_156:
	s_andn2_b64 vcc, exec, s[4:5]
	s_cbranch_vccnz .LBB0_9
	s_mul_i32 s4, s38, 0x1600000
	s_mul_hi_i32 s5, s38, 0x1600000
	s_add_u32 s4, s8, s4
	s_mul_i32 s28, s38, 3
	s_addc_u32 s5, s9, s5
	s_add_i32 s28, s28, -1
	s_lshl_b64 s[38:39], s[28:29], 12
	s_add_u32 s28, s6, s38
	s_addc_u32 s38, s7, s39
	s_cmpk_gt_i32 s55, 0x277f
	s_cselect_b32 s40, s28, 0
	s_mul_i32 s28, s42, 0xba3
	s_cselect_b32 s41, s38, 0
	s_lshr_b32 s38, s28, 31
	s_ashr_i32 s28, s28, 19
	s_add_i32 s28, s28, s38
	s_mul_i32 s38, s28, 0xb0
	s_sub_i32 s38, s42, s38
	s_sext_i32_i16 s39, s38
	s_lshl_b32 s38, s28, 6
	s_lshl_b32 s28, s39, 5
	s_and_b32 s42, s28, 0xe0
	s_cmpk_lt_u32 s42, 0x80
	s_cselect_b64 vcc, -1, 0
	s_lshl_b32 s39, s39, 4
	v_or_b32_e32 v6, s42, v74
	s_and_b32 s39, s39, 0xffffff80
	v_or_b32_e32 v8, s39, v6
	s_addk_i32 s39, 0xa80
	v_add_u32_e32 v6, s39, v6
	v_cndmask_b32_e32 v8, v6, v8, vcc
	v_ashrrev_i32_e32 v9, 31, v8
	v_or_b32_e32 v10, s38, v2
	v_lshl_add_u64 v[8:9], v[8:9], 2, s[4:5]
	v_or_b32_e32 v162, s38, v2
	v_mul_hi_i32_i24_e32 v165, 0x5800, v162
	v_mul_i32_i24_e32 v164, 0x5800, v162
	v_lshl_add_u64 v[164:165], v[8:9], 0, v[164:165]
	global_load_dword v114, v[164:165], off
	v_or_b32_e32 v163, s38, v13
	v_mul_hi_i32_i24_e32 v167, 0x5800, v163
	v_mul_i32_i24_e32 v166, 0x5800, v163
	v_lshl_add_u64 v[166:167], v[8:9], 0, v[166:167]
	global_load_dword v115, v[166:167], off
	v_or_b32_e32 v162, s38, v15
	v_mul_hi_i32_i24_e32 v165, 0x5800, v162
	v_mul_i32_i24_e32 v164, 0x5800, v162
	v_lshl_add_u64 v[164:165], v[8:9], 0, v[164:165]
	global_load_dword v116, v[164:165], off
	v_or_b32_e32 v163, s38, v17
	v_mul_hi_i32_i24_e32 v167, 0x5800, v163
	v_mul_i32_i24_e32 v166, 0x5800, v163
	v_lshl_add_u64 v[166:167], v[8:9], 0, v[166:167]
	global_load_dword v117, v[166:167], off
	v_or_b32_e32 v162, s38, v19
	v_mul_hi_i32_i24_e32 v165, 0x5800, v162
	v_mul_i32_i24_e32 v164, 0x5800, v162
	v_lshl_add_u64 v[164:165], v[8:9], 0, v[164:165]
	global_load_dword v118, v[164:165], off
	v_or_b32_e32 v163, s38, v21
	v_mul_hi_i32_i24_e32 v167, 0x5800, v163
	v_mul_i32_i24_e32 v166, 0x5800, v163
	v_lshl_add_u64 v[166:167], v[8:9], 0, v[166:167]
	global_load_dword v119, v[166:167], off
	v_or_b32_e32 v162, s38, v23
	v_mul_hi_i32_i24_e32 v165, 0x5800, v162
	v_mul_i32_i24_e32 v164, 0x5800, v162
	v_lshl_add_u64 v[164:165], v[8:9], 0, v[164:165]
	global_load_dword v120, v[164:165], off
	v_or_b32_e32 v163, s38, v25
	v_mul_hi_i32_i24_e32 v167, 0x5800, v163
	v_mul_i32_i24_e32 v166, 0x5800, v163
	v_lshl_add_u64 v[166:167], v[8:9], 0, v[166:167]
	global_load_dword v121, v[166:167], off
	v_or_b32_e32 v162, s38, v27
	v_mul_hi_i32_i24_e32 v165, 0x5800, v162
	v_mul_i32_i24_e32 v164, 0x5800, v162
	v_lshl_add_u64 v[164:165], v[8:9], 0, v[164:165]
	global_load_dword v122, v[164:165], off
	v_or_b32_e32 v163, s38, v29
	v_mul_hi_i32_i24_e32 v167, 0x5800, v163
	v_mul_i32_i24_e32 v166, 0x5800, v163
	v_lshl_add_u64 v[166:167], v[8:9], 0, v[166:167]
	global_load_dword v123, v[166:167], off
	v_or_b32_e32 v162, s38, v31
	v_mul_hi_i32_i24_e32 v165, 0x5800, v162
	v_mul_i32_i24_e32 v164, 0x5800, v162
	v_lshl_add_u64 v[164:165], v[8:9], 0, v[164:165]
	global_load_dword v124, v[164:165], off
	v_or_b32_e32 v163, s38, v33
	v_mul_hi_i32_i24_e32 v167, 0x5800, v163
	v_mul_i32_i24_e32 v166, 0x5800, v163
	v_lshl_add_u64 v[166:167], v[8:9], 0, v[166:167]
	global_load_dword v125, v[166:167], off
	v_or_b32_e32 v162, s38, v36
	v_mul_hi_i32_i24_e32 v165, 0x5800, v162
	v_mul_i32_i24_e32 v164, 0x5800, v162
	v_lshl_add_u64 v[164:165], v[8:9], 0, v[164:165]
	global_load_dword v126, v[164:165], off
	v_or_b32_e32 v163, s38, v38
	v_mul_hi_i32_i24_e32 v167, 0x5800, v163
	v_mul_i32_i24_e32 v166, 0x5800, v163
	v_lshl_add_u64 v[166:167], v[8:9], 0, v[166:167]
	global_load_dword v127, v[166:167], off
	v_or_b32_e32 v162, s38, v40
	v_mul_hi_i32_i24_e32 v165, 0x5800, v162
	v_mul_i32_i24_e32 v164, 0x5800, v162
	v_lshl_add_u64 v[164:165], v[8:9], 0, v[164:165]
	global_load_dword v128, v[164:165], off
	v_or_b32_e32 v163, s38, v42
	v_mul_hi_i32_i24_e32 v167, 0x5800, v163
	v_mul_i32_i24_e32 v166, 0x5800, v163
	v_lshl_add_u64 v[166:167], v[8:9], 0, v[166:167]
	global_load_dword v129, v[166:167], off
	v_or_b32_e32 v162, s38, v44
	v_mul_hi_i32_i24_e32 v165, 0x5800, v162
	v_mul_i32_i24_e32 v164, 0x5800, v162
	v_lshl_add_u64 v[164:165], v[8:9], 0, v[164:165]
	global_load_dword v130, v[164:165], off
	v_or_b32_e32 v163, s38, v46
	v_mul_hi_i32_i24_e32 v167, 0x5800, v163
	v_mul_i32_i24_e32 v166, 0x5800, v163
	v_lshl_add_u64 v[166:167], v[8:9], 0, v[166:167]
	global_load_dword v131, v[166:167], off
	v_or_b32_e32 v162, s38, v48
	v_mul_hi_i32_i24_e32 v165, 0x5800, v162
	v_mul_i32_i24_e32 v164, 0x5800, v162
	v_lshl_add_u64 v[164:165], v[8:9], 0, v[164:165]
	global_load_dword v132, v[164:165], off
	v_or_b32_e32 v163, s38, v50
	v_mul_hi_i32_i24_e32 v167, 0x5800, v163
	v_mul_i32_i24_e32 v166, 0x5800, v163
	v_lshl_add_u64 v[166:167], v[8:9], 0, v[166:167]
	global_load_dword v133, v[166:167], off
	v_or_b32_e32 v162, s38, v52
	v_mul_hi_i32_i24_e32 v165, 0x5800, v162
	v_mul_i32_i24_e32 v164, 0x5800, v162
	v_lshl_add_u64 v[164:165], v[8:9], 0, v[164:165]
	global_load_dword v134, v[164:165], off
	v_or_b32_e32 v163, s38, v54
	v_mul_hi_i32_i24_e32 v167, 0x5800, v163
	v_mul_i32_i24_e32 v166, 0x5800, v163
	v_lshl_add_u64 v[166:167], v[8:9], 0, v[166:167]
	global_load_dword v135, v[166:167], off
	v_or_b32_e32 v162, s38, v62
	v_mul_hi_i32_i24_e32 v165, 0x5800, v162
	v_mul_i32_i24_e32 v164, 0x5800, v162
	v_lshl_add_u64 v[164:165], v[8:9], 0, v[164:165]
	global_load_dword v136, v[164:165], off
	v_or_b32_e32 v163, s38, v63
	v_mul_hi_i32_i24_e32 v167, 0x5800, v163
; #define ALDS __attribute__((address_space(3)))
; template <bool F16> __device__ __forceinline__ void transpose_item(const float* W, int K, int N, int type, const float* gk, bf16* WT, ALDS float* scr, int item, int lane) {
;     const int nblk = N / 32, kb = item / nblk, nb = item % nblk, k0 = 64 * kb, n0 = 32 * nb;
;     const int sc = src_col(type, n0 + (lane & 31));
; #pragma unroll
;     for (int i = 0; i < 32; ++i) { const int kk = 2 * i + (lane >> 5); scr[kk * 33 + (lane & 31)] = W[(size_t)(k0 + kk) * N + sc] * (gk ? gk[k0 + kk] : 1.0f); }
;     asm volatile("s_waitcnt lgkmcnt(0)" ::: "memory");
	v_mul_i32_i24_e32 v166, 0x5800, v163
	v_lshl_add_u64 v[166:167], v[8:9], 0, v[166:167]
	global_load_dword v137, v[166:167], off
	v_or_b32_e32 v162, s38, v64
	v_mul_hi_i32_i24_e32 v165, 0x5800, v162
	v_mul_i32_i24_e32 v164, 0x5800, v162
	v_lshl_add_u64 v[164:165], v[8:9], 0, v[164:165]
	global_load_dword v138, v[164:165], off
	v_or_b32_e32 v163, s38, v65
	v_mul_hi_i32_i24_e32 v167, 0x5800, v163
	v_mul_i32_i24_e32 v166, 0x5800, v163
	v_lshl_add_u64 v[166:167], v[8:9], 0, v[166:167]
	global_load_dword v139, v[166:167], off
	v_or_b32_e32 v162, s38, v66
	v_mul_hi_i32_i24_e32 v165, 0x5800, v162
	v_mul_i32_i24_e32 v164, 0x5800, v162
	v_lshl_add_u64 v[164:165], v[8:9], 0, v[164:165]
	global_load_dword v140, v[164:165], off
	v_or_b32_e32 v163, s38, v67
	v_mul_hi_i32_i24_e32 v167, 0x5800, v163
	v_mul_i32_i24_e32 v166, 0x5800, v163
	v_lshl_add_u64 v[166:167], v[8:9], 0, v[166:167]
	global_load_dword v141, v[166:167], off
	v_or_b32_e32 v162, s38, v68
	v_mul_hi_i32_i24_e32 v165, 0x5800, v162
	v_mul_i32_i24_e32 v164, 0x5800, v162
	v_lshl_add_u64 v[164:165], v[8:9], 0, v[164:165]
	global_load_dword v142, v[164:165], off
	v_or_b32_e32 v163, s38, v69
	v_mul_hi_i32_i24_e32 v167, 0x5800, v163
	v_mul_i32_i24_e32 v166, 0x5800, v163
	v_lshl_add_u64 v[166:167], v[8:9], 0, v[166:167]
	global_load_dword v143, v[166:167], off
	v_or_b32_e32 v162, s38, v70
	v_mul_hi_i32_i24_e32 v165, 0x5800, v162
	v_mul_i32_i24_e32 v164, 0x5800, v162
	v_lshl_add_u64 v[164:165], v[8:9], 0, v[164:165]
	global_load_dword v144, v[164:165], off
	v_or_b32_e32 v163, s38, v71
	v_mul_hi_i32_i24_e32 v167, 0x5800, v163
	v_mul_i32_i24_e32 v166, 0x5800, v163
	v_lshl_add_u64 v[166:167], v[8:9], 0, v[166:167]
	global_load_dword v145, v[166:167], off
	s_cmp_lg_u64 s[40:41], 0
	s_cselect_b64 s[42:43], -1, 0
	s_ashr_i32 s39, s38, 31
	v_lshl_add_u64 v[166:167], s[38:39], 0, v[2:3]
	v_lshl_add_u64 v[166:167], v[166:167], 2, s[40:41]
	v_mov_b32_e32 v146, 1.0
	v_mov_b32_e32 v147, 1.0
	v_mov_b32_e32 v148, 1.0
	v_mov_b32_e32 v149, 1.0
	v_mov_b32_e32 v150, 1.0
	v_mov_b32_e32 v151, 1.0
	v_mov_b32_e32 v152, 1.0
	v_mov_b32_e32 v153, 1.0
	v_mov_b32_e32 v154, 1.0
	v_mov_b32_e32 v155, 1.0
	v_mov_b32_e32 v156, 1.0
	v_mov_b32_e32 v157, 1.0
	v_mov_b32_e32 v158, 1.0
	v_mov_b32_e32 v159, 1.0
	v_mov_b32_e32 v160, 1.0
	v_mov_b32_e32 v161, 1.0
	s_andn2_b64 vcc, exec, s[42:43]
	s_cbranch_vccnz .LtrC_nogk1
	global_load_dword v146, v[166:167], off
	global_load_dword v147, v[166:167], off offset:8
	global_load_dword v148, v[166:167], off offset:16
	global_load_dword v149, v[166:167], off offset:24
	global_load_dword v150, v[166:167], off offset:32
	global_load_dword v151, v[166:167], off offset:40
	global_load_dword v152, v[166:167], off offset:48
	global_load_dword v153, v[166:167], off offset:56
	global_load_dword v154, v[166:167], off offset:64
	global_load_dword v155, v[166:167], off offset:72
	global_load_dword v156, v[166:167], off offset:80
	global_load_dword v157, v[166:167], off offset:88
	global_load_dword v158, v[166:167], off offset:96
	global_load_dword v159, v[166:167], off offset:104
	global_load_dword v160, v[166:167], off offset:112
	global_load_dword v161, v[166:167], off offset:120
.LtrC_nogk1:
	s_waitcnt vmcnt(0)
	v_add_u32_e32 v168, v5, v58
	v_mul_f32_e32 v114, v114, v146
	v_add_u32_e32 v162, v5, v12
	ds_write_b32 v162, v114
	v_mul_f32_e32 v115, v115, v147
	v_add_u32_e32 v163, v5, v14
	ds_write_b32 v163, v115
	v_mul_f32_e32 v116, v116, v148
	v_add_u32_e32 v169, v5, v16
	ds_write_b32 v169, v116
	v_mul_f32_e32 v117, v117, v149
	v_add_u32_e32 v170, v5, v18
	ds_write_b32 v170, v117
	v_mul_f32_e32 v118, v118, v150
	v_add_u32_e32 v162, v5, v20
	ds_write_b32 v162, v118
	v_mul_f32_e32 v119, v119, v151
	v_add_u32_e32 v163, v5, v22
	ds_write_b32 v163, v119
	v_mul_f32_e32 v120, v120, v152
	v_add_u32_e32 v169, v5, v24
	ds_write_b32 v169, v120
	v_mul_f32_e32 v121, v121, v153
	v_add_u32_e32 v170, v5, v26
	ds_write_b32 v170, v121
	v_mul_f32_e32 v122, v122, v154
	v_add_u32_e32 v162, v5, v28
	ds_write_b32 v162, v122
	v_mul_f32_e32 v123, v123, v155
	v_add_u32_e32 v163, v5, v30
	ds_write_b32 v163, v123
	v_mul_f32_e32 v124, v124, v156
	v_add_u32_e32 v169, v5, v32
	ds_write_b32 v169, v124
	v_mul_f32_e32 v125, v125, v157
	v_add_u32_e32 v170, v5, v35
	ds_write_b32 v170, v125
	v_mul_f32_e32 v126, v126, v158
	v_add_u32_e32 v162, v5, v37
	ds_write_b32 v162, v126
	v_mul_f32_e32 v127, v127, v159
	v_add_u32_e32 v163, v5, v39
	ds_write_b32 v163, v127
	v_mul_f32_e32 v128, v128, v160
	v_add_u32_e32 v169, v5, v41
	ds_write_b32 v169, v128
	v_mul_f32_e32 v129, v129, v161
	v_add_u32_e32 v170, v5, v43
	ds_write_b32 v170, v129
	s_andn2_b64 vcc, exec, s[42:43]
	s_cbranch_vccnz .LtrC_nogk2
	global_load_dword v146, v[166:167], off offset:128
	global_load_dword v147, v[166:167], off offset:136
	global_load_dword v148, v[166:167], off offset:144
	global_load_dword v149, v[166:167], off offset:152
	global_load_dword v150, v[166:167], off offset:160
	global_load_dword v151, v[166:167], off offset:168
	global_load_dword v152, v[166:167], off offset:176
	global_load_dword v153, v[166:167], off offset:184
	global_load_dword v154, v[166:167], off offset:192
	global_load_dword v155, v[166:167], off offset:200
	global_load_dword v156, v[166:167], off offset:208
	global_load_dword v157, v[166:167], off offset:216
	global_load_dword v158, v[166:167], off offset:224
	global_load_dword v159, v[166:167], off offset:232
	global_load_dword v160, v[166:167], off offset:240
	global_load_dword v161, v[166:167], off offset:248
	s_waitcnt vmcnt(0)
.LtrC_nogk2:
	v_mul_f32_e32 v130, v130, v146
	v_add_u32_e32 v162, v5, v45
	ds_write_b32 v162, v130
	v_mul_f32_e32 v131, v131, v147
	v_add_u32_e32 v163, v5, v47
	ds_write_b32 v163, v131
	v_mul_f32_e32 v132, v132, v148
	v_add_u32_e32 v169, v5, v49
	ds_write_b32 v169, v132
	v_mul_f32_e32 v133, v133, v149
	v_add_u32_e32 v170, v5, v51
	ds_write_b32 v170, v133
	v_mul_f32_e32 v134, v134, v150
	v_add_u32_e32 v162, v5, v53
	ds_write_b32 v162, v134
	v_mul_f32_e32 v135, v135, v151
	v_add_u32_e32 v163, v5, v55
	ds_write_b32 v163, v135
	v_mul_f32_e32 v136, v136, v152
	v_add_u32_e32 v169, v5, v56
	ds_write_b32 v169, v136
	v_mul_f32_e32 v137, v137, v153
	v_add_u32_e32 v170, v5, v57
	ds_write_b32 v170, v137
	v_mul_f32_e32 v138, v138, v154
	v_add_u32_e32 v162, v5, v58
	ds_write_b32 v162, v138
	v_mul_f32_e32 v139, v139, v155
	ds_write_b32 v168, v139 offset:264
	v_mul_f32_e32 v140, v140, v156
	ds_write_b32 v168, v140 offset:528
	v_mul_f32_e32 v141, v141, v157
	ds_write_b32 v168, v141 offset:792
	v_mul_f32_e32 v142, v142, v158
	ds_write_b32 v168, v142 offset:1056
	v_mul_f32_e32 v143, v143, v159
	ds_write_b32 v168, v143 offset:1320
	v_mul_f32_e32 v144, v144, v160
	ds_write_b32 v168, v144 offset:1584
	v_mov_b32_e32 v8, v145
	v_mov_b32_e32 v9, v161
	v_add_u32_e32 v6, v5, v58
	s_branch .LBB0_8

; #define ALDS __attribute__((address_space(3)))
; template <int DV, bool BAND> ...
;     ...
;     for (int t = t0; t < t1; ++t) {
;         asm volatile("s_waitcnt vmcnt(%0)" :: "n"(NP) : "memory");
;         asm volatile("s_waitcnt lgkmcnt(0)\n\ts_barrier" ::: "memory");
;         const int tn = (t + 2 < t1) ? t + 2 : t1 - 1;
;         const ALDS unsigned char* sb = ring + s_cur;
;         f32x16 p0 = negm, p1 = negm;
;         bf16x8 kf[8];
; #pragma unroll
;         for (int d0 = 0; d0 < 4; ++d0) { kf[2 * d0] = *(const ALDS bf16x8*)(sb + ka + d0 * 2048); kf[2 * d0 + 1] = *(const ALDS bf16x8*)(sb + ka + d0 * 2048 + 512); }
;         s16x4 vlo[2][NDB], vhh[2][NDB];
; #pragma unroll
;         for (int db = 0; db < NDB; ++db) { vlo[0][db] = vtr(sb + va[db]); vhh[0][db] = vtr(sb + va[db] + 4 * ROWB); }
; #pragma unroll
;         for (int d0 = 0; d0 < 4; ++d0) {
;             p0 = __builtin_amdgcn_mfma_f32_32x32x16_bf16(kf[2 * d0], qr[d0], p0, 0, 0, 0);
;             p1 = __builtin_amdgcn_mfma_f32_32x32x16_bf16(kf[2 * d0 + 1], qr[d0], p1, 0, 0, 0);
;         }
;         __builtin_amdgcn_sched_barrier(0);
;         ATT_PIECE(0, tn, s_n2); ATT_PIECE(1, tn, s_n2); ATT_PIECE(2, tn, s_n2); ATT_PIECE(3, tn, s_n2);
;         __builtin_amdgcn_sched_barrier(0);
;         if (BAND) {
;             if (t == tq - 2 || t == tq + 2) {
;                 const int rel0 = t * 64 + 8 * hi - qpos;
; #pragma unroll
;                 for (int r = 0; r < 16; ++r) { const int rel = rel0 + 16 * (r >> 3) + (r & 7);
;                     if (rel < -128 || rel > 128) p0[r] = -INFINITY;
;                     if (rel + 32 < -128 || rel + 32 > 128) p1[r] = -INFINITY; }
;             }
;         }
;         float mx = fmaxf(p0[0], p1[0]);
; #pragma unroll
;         for (int r = 1; r < 16; ++r) mx = fmaxf(fmaxf(mx, p0[r]), p1[r]);
;         mx = halfswap_max(mx);
;         const bool first = (!BAND) && (t == t0);
;         const float dl = first ? mx : ((mx > THR) ? mx : 0.f);
;         if (__any(dl != 0.f)) {
;             m += dl;
; #pragma unroll
;             for (int r = 0; r < 16; ++r) { p0[r] -= dl; p1[r] -= dl; negm[r] = -m; }
;             const float f = first ? 1.f : __builtin_amdgcn_exp2f(-dl);
;             l *= f;
; #pragma unroll
;             for (int db = 0; db < NDB; ++db)
; #pragma unroll
;                 for (int r = 0; r < 16; ++r) o[db][r] *= f;
;         }
.LBB0_775:
	s_add_i32 s7, s6, 0
	s_waitcnt vmcnt(4)
	s_add_i32 s8, s7, s67
	s_waitcnt lgkmcnt(0)
	s_barrier
	s_setprio 1
	v_add3_u32 v0, s8, v153, v154
	ds_read_b128 v[82:85], v0
	ds_read_b128 v[130:133], v0 offset:512
	v_add_u32_e32 v164, s7, v155
	s_waitcnt lgkmcnt(1)
	v_mfma_f32_32x32x16_bf16 v[98:113], v[82:85], v[114:117], v[66:81]
	v_add_u32_e32 v161, s7, v157
	v_add_u32_e32 v163, s7, v156
	s_waitcnt lgkmcnt(0)
	v_mfma_f32_32x32x16_bf16 v[82:97], v[130:133], v[114:117], v[66:81]
	ds_read_b128 v[130:133], v0 offset:2048
	ds_read_b128 v[134:137], v0 offset:2560
	v_add_u32_e32 v162, s7, v158
	s_min_u32 s7, s4, 61
	s_waitcnt lgkmcnt(1)
	v_mfma_f32_32x32x16_bf16 v[98:113], v[130:133], v[118:121], v[98:113]
	s_waitcnt lgkmcnt(0)
	v_mfma_f32_32x32x16_bf16 v[82:97], v[134:137], v[118:121], v[82:97]
	ds_read_b128 v[130:133], v0 offset:4096
	ds_read_b128 v[134:137], v0 offset:4608
	ds_read_b128 v[166:169], v0 offset:6656
	s_waitcnt lgkmcnt(2)
	v_mfma_f32_32x32x16_bf16 v[98:113], v[130:133], v[122:125], v[98:113]
	ds_read_b128 v[130:133], v0 offset:6144
	ds_read_b64_tr_b16 v[142:143], v164 offset:16384
	ds_read_b64_tr_b16 v[144:145], v164 offset:17408
	ds_read_b64_tr_b16 v[138:139], v163
	ds_read_b64_tr_b16 v[140:141], v163 offset:1024
	s_waitcnt lgkmcnt(6)
	v_mfma_f32_32x32x16_bf16 v[82:97], v[134:137], v[122:125], v[82:97]
	s_waitcnt lgkmcnt(4)
	v_mfma_f32_32x32x16_bf16 v[98:113], v[130:133], v[126:129], v[98:113]
	ds_read_b64_tr_b16 v[134:135], v161
	ds_read_b64_tr_b16 v[136:137], v161 offset:1024
	ds_read_b64_tr_b16 v[130:131], v162
	ds_read_b64_tr_b16 v[132:133], v162 offset:1024
	v_mfma_f32_32x32x16_bf16 v[82:97], v[166:169], v[126:129], v[82:97]
	s_mul_i32 s7, s7, 0x48000
	s_add_u32 s7, s90, s7
	s_addc_u32 s12, s91, 0
	s_add_u32 s8, s7, 0x90000
	s_addc_u32 s9, s12, 0
	s_add_i32 s13, s5, s30
	s_mov_b32 s10, m0
	s_mov_b32 m0, s13
	s_nop 0
	global_load_lds_dwordx4 v151, s[8:9]
	s_mov_b32 m0, s10
	s_add_u32 s10, s7, 0x90080
	s_addc_u32 s11, s12, 0
	s_addk_i32 s13, 0x2000
	s_mov_b32 s14, m0
	s_mov_b32 m0, s13
	s_nop 0
	global_load_lds_dwordx4 v151, s[10:11]
	s_mov_b32 m0, s14
	s_add_i32 s10, s5, s84
	s_mov_b32 s11, m0
	s_mov_b32 m0, s10
	s_nop 0
	global_load_lds_dwordx4 v152, s[8:9]
	s_mov_b32 m0, s11
	s_add_u32 s8, s7, 0x94800
	s_addc_u32 s9, s12, 0
	s_addk_i32 s10, 0x400
	s_mov_b32 s7, m0
	s_mov_b32 m0, s10
	s_nop 0
	global_load_lds_dwordx4 v152, s[8:9]
	s_mov_b32 m0, s7
	v_max_f32_e32 v0, v82, v82
	v_max_f32_e32 v165, v98, v98
	v_max_f32_e32 v0, v165, v0
	v_max3_f32 v0, v0, v99, v83
	v_max3_f32 v0, v0, v100, v84
	v_max3_f32 v0, v0, v101, v85
	v_max3_f32 v0, v0, v102, v86
	v_max3_f32 v0, v0, v103, v87
	v_max3_f32 v0, v0, v104, v88
	v_max3_f32 v0, v0, v105, v89
	v_max3_f32 v0, v0, v106, v90
	v_max3_f32 v0, v0, v107, v91
	v_max3_f32 v0, v0, v108, v92
	v_max3_f32 v0, v0, v109, v93
	v_max3_f32 v0, v0, v110, v94
	v_max3_f32 v0, v0, v111, v95
	v_max3_f32 v0, v0, v112, v96
	v_max3_f32 v0, v0, v113, v97
	v_mov_b32_e32 v165, v0
	s_nop 1
	v_permlane32_swap_b32_e32 v0, v165
	v_max_f32_e32 v165, v165, v165
	v_max_f32_e32 v0, v0, v0
	v_max_f32_e32 v0, v0, v165
	v_cmp_lt_f32_e32 vcc, s31, v0
	s_cbranch_vccz .LBB0_774
	s_nop 1
	v_cndmask_b32_e32 v0, 0, v0, vcc
	s_nop 0
	v_exp_f32_e64 v68, -v0
	v_add_f32_e32 v159, v159, v0
	v_xor_b32_e32 v66, 0x80000000, v159
	v_pk_add_f32 v[98:99], v[98:99], v[0:1] op_sel_hi:[1,0] neg_lo:[0,1] neg_hi:[0,1]
	v_pk_add_f32 v[82:83], v[82:83], v[0:1] op_sel_hi:[1,0] neg_lo:[0,1] neg_hi:[0,1]
	v_pk_add_f32 v[100:101], v[100:101], v[0:1] op_sel_hi:[1,0] neg_lo:[0,1] neg_hi:[0,1]
	v_pk_add_f32 v[84:85], v[84:85], v[0:1] op_sel_hi:[1,0] neg_lo:[0,1] neg_hi:[0,1]
	v_pk_add_f32 v[102:103], v[102:103], v[0:1] op_sel_hi:[1,0] neg_lo:[0,1] neg_hi:[0,1]
	v_pk_add_f32 v[86:87], v[86:87], v[0:1] op_sel_hi:[1,0] neg_lo:[0,1] neg_hi:[0,1]
	v_pk_add_f32 v[104:105], v[104:105], v[0:1] op_sel_hi:[1,0] neg_lo:[0,1] neg_hi:[0,1]
	v_pk_add_f32 v[88:89], v[88:89], v[0:1] op_sel_hi:[1,0] neg_lo:[0,1] neg_hi:[0,1]
	v_pk_add_f32 v[106:107], v[106:107], v[0:1] op_sel_hi:[1,0] neg_lo:[0,1] neg_hi:[0,1]
	v_pk_add_f32 v[90:91], v[90:91], v[0:1] op_sel_hi:[1,0] neg_lo:[0,1] neg_hi:[0,1]
	v_pk_add_f32 v[108:109], v[108:109], v[0:1] op_sel_hi:[1,0] neg_lo:[0,1] neg_hi:[0,1]
	v_pk_add_f32 v[92:93], v[92:93], v[0:1] op_sel_hi:[1,0] neg_lo:[0,1] neg_hi:[0,1]
	v_pk_add_f32 v[110:111], v[110:111], v[0:1] op_sel_hi:[1,0] neg_lo:[0,1] neg_hi:[0,1]
	v_pk_add_f32 v[94:95], v[94:95], v[0:1] op_sel_hi:[1,0] neg_lo:[0,1] neg_hi:[0,1]
	v_pk_add_f32 v[112:113], v[112:113], v[0:1] op_sel_hi:[1,0] neg_lo:[0,1] neg_hi:[0,1]
	v_pk_add_f32 v[96:97], v[96:97], v[0:1] op_sel_hi:[1,0] neg_lo:[0,1] neg_hi:[0,1]
	v_pk_mul_f32 v[64:65], v[64:65], v[68:69] op_sel_hi:[1,0]
	v_pk_mul_f32 v[62:63], v[62:63], v[68:69] op_sel_hi:[1,0]
	v_pk_mul_f32 v[60:61], v[60:61], v[68:69] op_sel_hi:[1,0]
	v_pk_mul_f32 v[58:59], v[58:59], v[68:69] op_sel_hi:[1,0]
	v_pk_mul_f32 v[56:57], v[56:57], v[68:69] op_sel_hi:[1,0]
	v_pk_mul_f32 v[54:55], v[54:55], v[68:69] op_sel_hi:[1,0]
	v_pk_mul_f32 v[52:53], v[52:53], v[68:69] op_sel_hi:[1,0]
	v_pk_mul_f32 v[50:51], v[50:51], v[68:69] op_sel_hi:[1,0]
	v_pk_mul_f32 v[48:49], v[48:49], v[68:69] op_sel_hi:[1,0]
	v_pk_mul_f32 v[46:47], v[46:47], v[68:69] op_sel_hi:[1,0]
	v_pk_mul_f32 v[44:45], v[44:45], v[68:69] op_sel_hi:[1,0]
	v_pk_mul_f32 v[42:43], v[42:43], v[68:69] op_sel_hi:[1,0]
	v_pk_mul_f32 v[40:41], v[40:41], v[68:69] op_sel_hi:[1,0]
	v_pk_mul_f32 v[38:39], v[38:39], v[68:69] op_sel_hi:[1,0]
	v_pk_mul_f32 v[36:37], v[36:37], v[68:69] op_sel_hi:[1,0]
	v_pk_mul_f32 v[34:35], v[34:35], v[68:69] op_sel_hi:[1,0]
	v_pk_mul_f32 v[32:33], v[32:33], v[68:69] op_sel_hi:[1,0]
	v_pk_mul_f32 v[30:31], v[30:31], v[68:69] op_sel_hi:[1,0]
	v_pk_mul_f32 v[28:29], v[28:29], v[68:69] op_sel_hi:[1,0]
	v_pk_mul_f32 v[26:27], v[26:27], v[68:69] op_sel_hi:[1,0]
	v_pk_mul_f32 v[24:25], v[24:25], v[68:69] op_sel_hi:[1,0]
	v_pk_mul_f32 v[22:23], v[22:23], v[68:69] op_sel_hi:[1,0]
	v_pk_mul_f32 v[20:21], v[20:21], v[68:69] op_sel_hi:[1,0]
	v_pk_mul_f32 v[18:19], v[18:19], v[68:69] op_sel_hi:[1,0]
	v_pk_mul_f32 v[16:17], v[16:17], v[68:69] op_sel_hi:[1,0]
	v_pk_mul_f32 v[14:15], v[14:15], v[68:69] op_sel_hi:[1,0]
	v_pk_mul_f32 v[12:13], v[12:13], v[68:69] op_sel_hi:[1,0]
	v_pk_mul_f32 v[10:11], v[10:11], v[68:69] op_sel_hi:[1,0]
	v_pk_mul_f32 v[8:9], v[8:9], v[68:69] op_sel_hi:[1,0]
	v_pk_mul_f32 v[6:7], v[6:7], v[68:69] op_sel_hi:[1,0]
	v_pk_mul_f32 v[4:5], v[4:5], v[68:69] op_sel_hi:[1,0]
	v_pk_mul_f32 v[2:3], v[2:3], v[68:69] op_sel_hi:[1,0]
	v_mul_f32_e32 v160, v160, v68
	v_mov_b32_e32 v67, v66
	v_mov_b32_e32 v68, v66
	v_mov_b32_e32 v69, v66
	v_mov_b32_e32 v70, v66
	v_mov_b32_e32 v71, v66
	v_mov_b32_e32 v72, v66
	v_mov_b32_e32 v73, v66
	v_mov_b32_e32 v74, v66
	v_mov_b32_e32 v75, v66
	v_mov_b32_e32 v76, v66
	v_mov_b32_e32 v77, v66
	v_mov_b32_e32 v78, v66
	v_mov_b32_e32 v79, v66
	v_mov_b32_e32 v80, v66
	v_mov_b32_e32 v81, v66
	s_branch .LBB0_774
